# sample attention: the 4 waves of a key split each load a quarter of the K tile and share it through a double-buffered LDS tile with one workgroup barrier per step (was: every wave loaded the whole til
# speedup vs baseline: 1.0090x; 1.0090x over previous
; #define LAS __attribute__((address_space(3)))
; __device__ __forceinline__ void sattn_unit(const Args& a, LAS unsigned char* lds, const LAS float* bt, int db, int h, int t, int tid, int wave, int lane) {
;     ...
;     bf16x8 qr[4];
;     { const bf16* qp = Qb + (size_t)(MP + db * 64 + qg * 32 + r32) * 1024 + h * 128 + t * 64 + hi * 8;
; #pragma unroll
;       for (int d0 = 0; d0 < 4; ++d0) qr[d0] = *(const bf16x8*)(qp + d0 * 16); }
;     float m = -1e30f, l = 0.f; f32x16 o[2];
;     o[0] = f32x16{}; o[1] = f32x16{};
;     const unsigned klo = (unsigned)(r32 * 1024 + hi * 8), vlo = (unsigned)(hi * 4096 + dvh * 64 + r32), kco = (unsigned)((lane >> 4) * 1024 + (lane & 15) * 4);
;     LAS float* kst = (LAS float*)(lds + 40960 + wave * 8704);
;     f32x4 kr[8]; float vr[2][16];
.LBB0_294:
	s_ashr_i32 s0, s90, 4
	s_lshl_b32 s4, s0, 6
	v_mbcnt_lo_u32_b32 v16, -1, 0
	v_mbcnt_hi_u32_b32 v16, -1, v16
	s_add_i32 s6, s4, 0x8000
	v_add_u32_e32 v0, s11, v16
	s_or_b32 s78, s6, s85
	v_and_b32_e32 v159, 31, v16
	v_or_b32_e32 v0, s78, v159
	s_lshl_b32 s30, s0, 11
	v_ashrrev_i32_e32 v1, 31, v0
	v_readlane_b32 s48, v251, 36
	s_add_i32 s0, s30, s95
	s_bfe_u32 s14, s90, 0x30001
	v_lshlrev_b64 v[0:1], 11, v[0:1]
	v_readlane_b32 s49, v251, 37
	s_ashr_i32 s1, s0, 31
	s_and_b32 s15, s90, 1
	v_lshl_add_u64 v[0:1], s[48:49], 0, v[0:1]
	s_lshl_b32 s20, s14, 8
	s_lshl_b64 s[0:1], s[0:1], 12
	s_lshl_b32 s79, s14, 9
	s_lshl_b32 s5, s14, 7
	v_lshl_add_u64 v[0:1], v[0:1], 0, s[20:21]
	s_lshl_b32 s7, s15, 6
	s_lshl_b32 s20, s15, 7
	s_or_b32 s0, s0, s79
	v_ashrrev_i32_e32 v17, 5, v16
	s_mul_i32 s34, s14, 0x310
	v_lshlrev_b32_e32 v160, 2, v16
	s_add_u32 s14, s40, s0
	v_lshl_add_u64 v[0:1], v[0:1], 0, s[20:21]
	v_lshlrev_b32_e32 v114, 3, v17
	v_ashrrev_i32_e32 v18, 4, v16
	v_and_b32_e32 v19, 60, v160
	s_addc_u32 s35, s41, s1
	s_lshl_b32 s20, s15, 8
	v_ashrrev_i32_e32 v115, 31, v114
	v_lshl_or_b32 v112, v18, 10, v19
	s_add_u32 s92, s14, s20
	v_lshl_add_u64 v[0:1], v[114:115], 1, v[0:1]
	s_addc_u32 s93, s35, 0
	v_add_u32_e32 v120, 0x1000, v112
	v_mov_b32_e32 v121, v113
	global_load_dwordx4 v[60:63], v[0:1], off
	global_load_dwordx4 v[56:59], v[0:1], off offset:32
	global_load_dwordx4 v[52:55], v[0:1], off offset:64
	global_load_dwordx4 v[48:51], v[0:1], off offset:96
	v_lshl_add_u64 v[0:1], v[112:113], 2, s[92:93]
	v_lshl_add_u64 v[2:3], v[120:121], 2, s[92:93]
	v_add_u32_e32 v122, 0x2000, v112
	v_mov_b32_e32 v123, v113
	v_add_u32_e32 v124, 0x3000, v112
	v_mov_b32_e32 v125, v113
	global_load_dwordx4 v[64:67], v[0:1], off
	global_load_dwordx4 v[68:71], v[2:3], off
	v_lshl_add_u64 v[0:1], v[122:123], 2, s[92:93]
	v_lshl_add_u64 v[2:3], v[124:125], 2, s[92:93]
	v_add_u32_e32 v126, 0x4000, v112
	v_mov_b32_e32 v127, v113
	v_add_u32_e32 v128, 0x5000, v112
	v_mov_b32_e32 v129, v113
	global_load_dwordx4 v[72:75], v[0:1], off
	global_load_dwordx4 v[76:79], v[2:3], off
	v_lshl_add_u64 v[0:1], v[126:127], 2, s[92:93]
	v_lshl_add_u64 v[2:3], v[128:129], 2, s[92:93]
	v_add_u32_e32 v130, 0x6000, v112
	v_mov_b32_e32 v131, v113
	v_add_u32_e32 v132, 0x7000, v112
	v_mov_b32_e32 v133, v113
	global_load_dwordx4 v[80:83], v[0:1], off
	global_load_dwordx4 v[84:87], v[2:3], off
	v_lshl_add_u64 v[0:1], v[130:131], 2, s[92:93]
	v_lshl_add_u64 v[2:3], v[132:133], 2, s[92:93]
	s_add_i32 s92, s34, 0
	s_add_i32 s92, s92, 0x1f000
	v_lshlrev_b32_e32 v4, 12, v17
	s_add_u32 s0, s42, s0
	v_or3_b32 v116, v4, s91, v159
	s_addc_u32 s1, s43, s1
	v_mov_b32_e32 v117, v113
	s_add_u32 vcc_lo, s0, 0x10000
	v_or_b32_e32 v118, 32, v116
	v_mov_b32_e32 v119, v113
	s_addc_u32 vcc_hi, s1, 0
	v_lshlrev_b64 v[134:135], 2, v[116:117]
	v_lshlrev_b64 v[136:137], 2, v[118:119]
	global_load_dwordx4 v[88:91], v[0:1], off
	global_load_dwordx4 v[92:95], v[2:3], off
	v_lshl_add_u64 v[2:3], vcc, 0, v[134:135]
	v_lshl_add_u64 v[4:5], vcc, 0, v[136:137]
	s_add_u32 vcc_lo, s0, 0x1000
	s_addc_u32 vcc_hi, s1, 0
	s_add_u32 s34, s0, 0x11000
	s_addc_u32 s35, s1, 0
	v_lshl_add_u64 v[8:9], s[34:35], 0, v[134:135]
	v_lshl_add_u64 v[12:13], s[34:35], 0, v[136:137]
	s_add_u32 s34, s0, 0x2000
	s_addc_u32 s35, s1, 0
	v_lshl_add_u64 v[6:7], vcc, 0, v[134:135]
	v_lshl_add_u64 v[10:11], vcc, 0, v[136:137]
	s_add_u32 vcc_lo, s0, 0x12000
	v_lshl_add_u64 v[0:1], s[0:1], 0, v[134:135]
	s_addc_u32 vcc_hi, s1, 0
	global_load_dword v201, v[0:1], off
	global_load_dword v196, v[2:3], off
	global_load_dword v181, v[4:5], off
	global_load_dword v203, v[6:7], off
	global_load_dword v197, v[8:9], off
	global_load_dword v185, v[10:11], off
	global_load_dword v182, v[12:13], off
	global_load_dword v187, v[0:1], off offset:128
	v_lshl_add_u64 v[0:1], s[34:35], 0, v[134:135]
	v_lshl_add_u64 v[4:5], s[34:35], 0, v[136:137]
	s_add_u32 s34, s0, 0x3000
	s_addc_u32 s35, s1, 0
	v_lshl_add_u64 v[2:3], vcc, 0, v[134:135]
	v_lshl_add_u64 v[6:7], vcc, 0, v[136:137]
	s_add_u32 vcc_lo, s0, 0x13000
	s_addc_u32 vcc_hi, s1, 0
	v_lshl_add_u64 v[8:9], s[34:35], 0, v[134:135]
	v_lshl_add_u64 v[12:13], s[34:35], 0, v[136:137]
	s_add_u32 s34, s0, 0x8000
	s_addc_u32 s35, s1, 0
	v_lshl_add_u64 v[10:11], vcc, 0, v[134:135]
	v_lshl_add_u64 v[14:15], vcc, 0, v[136:137]
	s_add_u32 vcc_lo, s0, 0x18000
	s_addc_u32 vcc_hi, s1, 0
	global_load_dword v212, v[0:1], off
	global_load_dword v208, v[2:3], off
	global_load_dword v205, v[4:5], off
	global_load_dword v198, v[6:7], off
	global_load_dword v213, v[8:9], off
	global_load_dword v209, v[10:11], off
	global_load_dword v206, v[12:13], off
	global_load_dword v199, v[14:15], off
	v_lshl_add_u64 v[0:1], s[34:35], 0, v[134:135]
	v_lshl_add_u64 v[4:5], s[34:35], 0, v[136:137]
	s_add_u32 s34, s0, 0x9000
	s_addc_u32 s35, s1, 0
	v_lshl_add_u64 v[2:3], vcc, 0, v[134:135]
	v_lshl_add_u64 v[6:7], vcc, 0, v[136:137]
	s_add_u32 vcc_lo, s0, 0x19000
	s_addc_u32 vcc_hi, s1, 0
	v_lshl_add_u64 v[8:9], s[34:35], 0, v[134:135]
	v_lshl_add_u64 v[12:13], s[34:35], 0, v[136:137]
	s_add_u32 s34, s0, 0xa000
	s_addc_u32 s35, s1, 0
	v_lshl_add_u64 v[10:11], vcc, 0, v[134:135]
	v_lshl_add_u64 v[14:15], vcc, 0, v[136:137]
	s_add_u32 vcc_lo, s0, 0x1a000
	s_addc_u32 vcc_hi, s1, 0
	global_load_dword v225, v[0:1], off
	global_load_dword v220, v[2:3], off
	global_load_dword v215, v[4:5], off
	global_load_dword v210, v[6:7], off
	global_load_dword v227, v[8:9], off
	global_load_dword v221, v[10:11], off
	global_load_dword v217, v[12:13], off
	global_load_dword v211, v[14:15], off
	v_lshl_add_u64 v[0:1], s[34:35], 0, v[134:135]
; #define LAS __attribute__((address_space(3)))
; __device__ __forceinline__ void sattn_unit(const Args& a, LAS unsigned char* lds, const LAS float* bt, int db, int h, int t, int tid, int wave, int lane) {
;     ...
;     float m = -1e30f, l = 0.f; f32x16 o[2];
;     o[0] = f32x16{}; o[1] = f32x16{};
;     const unsigned klo = (unsigned)(r32 * 1024 + hi * 8), vlo = (unsigned)(hi * 4096 + dvh * 64 + r32), kco = (unsigned)((lane >> 4) * 1024 + (lane & 15) * 4);
;     LAS float* kst = (LAS float*)(lds + 40960 + wave * 8704);
;     f32x4 kr[8]; float vr[2][16];
	v_lshl_add_u64 v[4:5], s[34:35], 0, v[136:137]
	s_add_u32 s34, s0, 0xb000
	s_addc_u32 s35, s1, 0
	s_add_u32 s0, s0, 0x1b000
	s_addc_u32 s1, s1, 0
	v_lshl_add_u64 v[2:3], vcc, 0, v[134:135]
	v_lshl_add_u64 v[6:7], vcc, 0, v[136:137]
	v_lshl_add_u64 v[8:9], s[34:35], 0, v[134:135]
	v_lshl_add_u64 v[10:11], s[0:1], 0, v[134:135]
	v_lshl_add_u64 v[12:13], s[34:35], 0, v[136:137]
	v_lshl_add_u64 v[14:15], s[0:1], 0, v[136:137]
	global_load_dword v234, v[0:1], off
	global_load_dword v232, v[2:3], off
	global_load_dword v229, v[4:5], off
	global_load_dword v222, v[6:7], off
	global_load_dword v235, v[8:9], off
	global_load_dword v233, v[10:11], off
	global_load_dword v230, v[12:13], off
	global_load_dword v223, v[14:15], off
	v_mul_u32_u24_e32 v0, 0x110, v159
	v_and_b32_e32 v1, 0xffffffe0, v16
	v_add3_u32 v170, s94, v0, v1
	v_or_b32_e32 v0, s85, v159
	v_lshlrev_b32_e32 v163, 2, v17
	v_sub_u32_e32 v168, v163, v0
	v_and_or_b32 v0, v163, 60, v191
	v_add_u32_e32 v161, 8, v163
	v_lshlrev_b32_e32 v164, 2, v0
	v_and_or_b32 v0, v161, 60, v191
	v_add_u32_e32 v157, 9, v163
	v_lshlrev_b32_e32 v162, 2, v0
	v_and_or_b32 v0, v157, 61, v191
	v_add_u32_e32 v155, 10, v163
	v_lshlrev_b32_e32 v158, 2, v0
	v_and_or_b32 v0, v155, 62, v191
	v_add_u32_e32 v153, 11, v163
	v_lshlrev_b32_e32 v156, 2, v0
	v_and_or_b32 v0, v153, 63, v191
	v_add_u32_e32 v151, 16, v163
	v_lshlrev_b32_e32 v154, 2, v0
	v_and_or_b32 v0, v151, 60, v191
	v_add_u32_e32 v149, 17, v163
	v_lshlrev_b32_e32 v152, 2, v0
	v_and_or_b32 v0, v149, 61, v191
	v_add_u32_e32 v147, 18, v163
	v_lshlrev_b32_e32 v150, 2, v0
	v_and_or_b32 v0, v147, 62, v191
	v_add_u32_e32 v145, 19, v163
	v_lshlrev_b32_e32 v148, 2, v0
	v_and_or_b32 v0, v145, 63, v191
	v_add_u32_e32 v143, 24, v163
	v_lshlrev_b32_e32 v146, 2, v0
	v_and_or_b32 v0, v143, 60, v191
	v_add_u32_e32 v141, 25, v163
	v_lshlrev_b32_e32 v144, 2, v0
	v_and_or_b32 v0, v141, 61, v191
	v_add_u32_e32 v139, 26, v163
	v_cmp_lt_i32_e32 vcc, v190, v192
	s_movk_i32 s0, 0x110
	v_lshlrev_b32_e32 v142, 2, v0
	v_and_or_b32 v0, v139, 62, v191
	v_add_u32_e32 v115, 27, v163
	s_waitcnt vmcnt(45)
	v_lshl_add_u32 v32, v19, 2, s94
	s_add_u32 s93, s40, s20
	v_cndmask_b32_e32 v1, v189, v190, vcc
	v_mul_lo_u32 v33, v18, s0
	v_lshlrev_b32_e32 v140, 2, v0
	v_and_or_b32 v0, v115, 63, v191
	s_addc_u32 s89, s41, 0
	s_mov_b32 s35, 0
	v_lshlrev_b32_e32 v194, 2, v1
	s_or_b32 s30, s30, 32
	v_add_u32_e32 v171, 0xfffff880, v168
	v_or_b32_e32 v165, 4, v164
	v_or_b32_e32 v166, 8, v164
	v_or_b32_e32 v167, 12, v164
	v_lshlrev_b32_e32 v138, 2, v0
	v_mov_b32_e32 v0, v113
	v_mov_b32_e32 v1, v113
	v_mov_b32_e32 v2, v113
	v_mov_b32_e32 v3, v113
	v_mov_b32_e32 v4, v113
	v_mov_b32_e32 v5, v113
	v_mov_b32_e32 v6, v113
	v_mov_b32_e32 v7, v113
	v_mov_b32_e32 v8, v113
	v_mov_b32_e32 v9, v113
	v_mov_b32_e32 v10, v113
	v_mov_b32_e32 v11, v113
	v_mov_b32_e32 v12, v113
	v_mov_b32_e32 v13, v113
	v_mov_b32_e32 v14, v113
	v_mov_b32_e32 v15, v113
	v_mov_b32_e32 v16, v113
	v_mov_b32_e32 v17, v113
	v_mov_b32_e32 v18, v113
	v_mov_b32_e32 v19, v113
	v_mov_b32_e32 v20, v113
	v_mov_b32_e32 v21, v113
	v_mov_b32_e32 v22, v113
	v_mov_b32_e32 v23, v113
	v_mov_b32_e32 v24, v113
	v_mov_b32_e32 v25, v113
	v_mov_b32_e32 v26, v113
	v_mov_b32_e32 v27, v113
	v_mov_b32_e32 v28, v113
	v_mov_b32_e32 v29, v113
	v_mov_b32_e32 v30, v113
	v_mov_b32_e32 v31, v113
	v_mov_b32_e32 v169, 0
	v_mov_b32_e32 v244, 0xf149f2ca
	v_add_u32_e32 v172, v32, v33
	s_waitcnt vmcnt(0)
	v_mov_b32_e32 v243, v223
	v_mov_b32_e32 v236, v222
	v_mov_b32_e32 v231, v211
	v_mov_b32_e32 v214, v210
	v_mov_b32_e32 v207, v199
	v_mov_b32_e32 v183, v198
	v_mov_b32_e32 v180, v182
	v_mov_b32_e32 v173, v181
	v_mov_b32_e32 v240, v230
	v_mov_b32_e32 v237, v229
	v_mov_b32_e32 v224, v217
	v_mov_b32_e32 v216, v215
	v_mov_b32_e32 v200, v206
	v_mov_b32_e32 v184, v205
	v_mov_b32_e32 v177, v185
	v_mov_b32_e32 v174, v187
	v_mov_b32_e32 v241, v233
	v_mov_b32_e32 v238, v232
	v_mov_b32_e32 v226, v221
	v_mov_b32_e32 v218, v220
	v_mov_b32_e32 v202, v209
	v_mov_b32_e32 v186, v208
	v_mov_b32_e32 v178, v197
	v_mov_b32_e32 v175, v196
	v_mov_b32_e32 v242, v235
	v_mov_b32_e32 v239, v234
	v_mov_b32_e32 v228, v227
	v_mov_b32_e32 v219, v225
	v_mov_b32_e32 v204, v213
	v_mov_b32_e32 v195, v212
	v_mov_b32_e32 v179, v203
	v_mov_b32_e32 v176, v201
	v_readlane_b32 s32, v251, 10
	s_and_b32 s81, s32, 3
	s_lshr_b32 s32, s32, 2
	s_mul_i32 s32, s32, 0x4400
	s_sub_i32 s32, s32, s94
	s_mul_i32 s34, s81, 0x880
	s_add_i32 s34, s34, s32
	v_add_u32_e32 v170, s32, v170
	v_add_u32_e32 v172, s34, v172
	s_cmp_eq_u32 s81, 0
	s_cbranch_scc1 .Lks_m0
	s_cmp_eq_u32 s81, 1
	s_cbranch_scc1 .Lks_m1
	s_cmp_eq_u32 s81, 2
	s_cbranch_scc1 .Lks_m2
	v_mov_b32_e32 v64, v88
	v_mov_b32_e32 v65, v89
	v_mov_b32_e32 v66, v90
	v_mov_b32_e32 v67, v91
	v_mov_b32_e32 v68, v92
	v_mov_b32_e32 v69, v93
	v_mov_b32_e32 v70, v94
	v_mov_b32_e32 v71, v95
	s_branch .Lks_m0
; __device__ __forceinline__ void sattn_unit(const Args& a, LAS unsigned char* lds, const LAS float* bt, int db, int h, int t, int tid, int wave, int lane) {
;     ...
;     for (int it = 0; it < nf; ++it) {
;         const int key0 = __builtin_amdgcn_readfirstlane((tile0 + it) * 32);
;         bf16x8 kf[4]; bf16x8 vf[2][2];
;         SA_CVT();
;         if (it + 1 < nf) SA_LOAD(key0 + 32);
.Lks_m1:
	v_mov_b32_e32 v64, v72
	v_mov_b32_e32 v65, v73
	v_mov_b32_e32 v66, v74
	v_mov_b32_e32 v67, v75
	v_mov_b32_e32 v68, v76
	v_mov_b32_e32 v69, v77
	v_mov_b32_e32 v70, v78
	v_mov_b32_e32 v71, v79
	s_branch .Lks_m0
.Lks_m2:
	v_mov_b32_e32 v64, v80
	v_mov_b32_e32 v65, v81
	v_mov_b32_e32 v66, v82
	v_mov_b32_e32 v67, v83
	v_mov_b32_e32 v68, v84
	v_mov_b32_e32 v69, v85
	v_mov_b32_e32 v70, v86
	v_mov_b32_e32 v71, v87
.Lks_m0:
	s_lshl_b32 s81, s81, 15
	s_movk_i32 s32, 0x2200
.LBB0_295:
	ds_write_b128 v172, v[64:67] offset:40960
	ds_write_b128 v172, v[68:71] offset:42048
	s_waitcnt lgkmcnt(0)
	s_barrier
	ds_read_b128 v[108:111], v170 offset:40960
	ds_read_b128 v[104:107], v170 offset:40976
	ds_read_b128 v[100:103], v170 offset:41024
	ds_read_b128 v[96:99], v170 offset:41040
	ds_read_b128 v[44:47], v170 offset:41088
	ds_read_b128 v[40:43], v170 offset:41104
	ds_read_b128 v[36:39], v170 offset:41152
	ds_read_b128 v[32:35], v170 offset:41168
	v_add_u32_e32 v170, s32, v170
	v_add_u32_e32 v172, s32, v172
	s_sub_i32 s32, 0, s32
	s_add_i32 s0, s96, s35
	s_lshl_b32 vcc_lo, s0, 5
	s_add_i32 s35, s35, 1
	s_cmp_ge_u32 s35, s97
	s_cbranch_scc1 .LBB0_297
	s_add_i32 s0, s30, vcc_lo
	s_ashr_i32 s1, s0, 31
	s_lshl_b64 s[0:1], s[0:1], 12
	s_lshl_b32 s14, s5, 2
	s_or_b32 s0, s0, s14
	s_add_u32 s48, s93, s0
	s_addc_u32 s49, s89, s1
	s_add_u32 s48, s48, s81
	s_addc_u32 s49, s49, 0
	s_add_u32 s0, s42, s0
	s_addc_u32 s1, s43, s1
	v_lshl_add_u64 v[64:65], v[112:113], 2, s[48:49]
	v_lshl_add_u64 v[68:69], v[120:121], 2, s[48:49]
	s_nop 0
	s_nop 0
	s_nop 0
	s_nop 0
	s_nop 0
	s_nop 0
	global_load_dwordx4 v[64:67], v[64:65], off
	s_nop 0
	global_load_dwordx4 v[68:71], v[68:69], off
	s_nop 0
	s_nop 0
	s_nop 0
	s_nop 0
	s_nop 0
	s_nop 0
	s_nop 0
	s_nop 0
	s_nop 0
	s_nop 0
	s_nop 0
	s_nop 0
	s_nop 0
	global_load_dword v176, v134, s[0:1]
	global_load_dword v174, v134, s[0:1] offset:128
	s_add_u32 s14, s0, 0x10000
	s_addc_u32 s15, s1, 0
	global_load_dword v175, v134, s[14:15]
	global_load_dword v173, v136, s[14:15]
	s_add_u32 s48, s0, 0x1000
	s_addc_u32 s49, s1, 0
	global_load_dword v179, v134, s[48:49]
	global_load_dword v177, v136, s[48:49]
	s_add_u32 s14, s0, 0x11000
	s_addc_u32 s15, s1, 0
	global_load_dword v178, v134, s[14:15]
	global_load_dword v180, v136, s[14:15]
	s_add_u32 s48, s0, 0x2000
	s_addc_u32 s49, s1, 0
	global_load_dword v195, v134, s[48:49]
	global_load_dword v184, v136, s[48:49]
	s_add_u32 s14, s0, 0x12000
	s_addc_u32 s15, s1, 0
	global_load_dword v186, v134, s[14:15]
	global_load_dword v183, v136, s[14:15]
	s_add_u32 s48, s0, 0x3000
	s_addc_u32 s49, s1, 0
	global_load_dword v204, v134, s[48:49]
	global_load_dword v200, v136, s[48:49]
	s_add_u32 s14, s0, 0x13000
	s_addc_u32 s15, s1, 0
	global_load_dword v202, v134, s[14:15]
	global_load_dword v207, v136, s[14:15]
	s_add_u32 s48, s0, 0x8000
	s_addc_u32 s49, s1, 0
	global_load_dword v219, v134, s[48:49]
	global_load_dword v216, v136, s[48:49]
	s_add_u32 s14, s0, 0x18000
	s_addc_u32 s15, s1, 0
	global_load_dword v218, v134, s[14:15]
	global_load_dword v214, v136, s[14:15]
	s_add_u32 s48, s0, 0x9000
	s_addc_u32 s49, s1, 0
	global_load_dword v228, v134, s[48:49]
	global_load_dword v224, v136, s[48:49]
	s_add_u32 s14, s0, 0x19000
	s_addc_u32 s15, s1, 0
	global_load_dword v226, v134, s[14:15]
	global_load_dword v231, v136, s[14:15]
	s_add_u32 s48, s0, 0xa000
	s_addc_u32 s49, s1, 0
	global_load_dword v239, v134, s[48:49]
	global_load_dword v237, v136, s[48:49]
	s_add_u32 s14, s0, 0x1a000
	s_addc_u32 s15, s1, 0
	global_load_dword v238, v134, s[14:15]
	global_load_dword v236, v136, s[14:15]
	s_add_u32 s48, s0, 0xb000
	s_addc_u32 s49, s1, 0
	global_load_dword v242, v134, s[48:49]
	global_load_dword v240, v136, s[48:49]
	s_add_u32 s14, s0, 0x1b000
	s_addc_u32 s15, s1, 0
	global_load_dword v241, v134, s[14:15]
	global_load_dword v243, v136, s[14:15]

; __device__ __forceinline__ int crow(int r,int hi){return (r&3)+8*(r>>2)+4*hi;}
; __device__ __forceinline__ int crow(int r, int hi) { return (r & 3) + 8 * (r >> 2) + 4 * hi; }
; __device__ __forceinline__ void sattn_unit(const Args& a, LAS unsigned char* lds, const LAS float* bt, int db, int h, int t, int tid, int wave, int lane) {
;     ...
;     if (ksp == 1) {
;         for (int it = 0; it < 2; ++it) {
;             const int key0 = 2048 + it * 32;
;             bf16x8 kf[4]; bf16x8 vf[2][2];
;             const bf16* kpu = Kb + (size_t)(MP + db * 64 + key0 - 2048) * 1024 + h * 128 + t * 64;
;             const bf16* vpu = Vb + (size_t)(MP + db * 64 + key0 - 2048) * 1024 + h * 128;
; #pragma unroll
;             for (int d0 = 0; d0 < 4; ++d0) kf[d0] = *(const bf16x8*)(kpu + (klo + d0 * 16));
; #pragma unroll
;             for (int e = 0; e < 8; ++e) { const bf16* r0 = vpu + crow(e, 0) * 1024; const bf16* r1 = vpu + (16 + crow(e, 0)) * 1024;
; #pragma unroll
;                 for (int d2 = 0; d2 < 2; ++d2) { vf[d2][0][e] = (short)r0[vlo + d2 * 32]; vf[d2][1][e] = (short)r1[vlo + d2 * 32]; } }
;             SA_COMPUTE(key0);
.LBB0_303:
	v_cndmask_b32_e64 v32, 0, 1, s[26:27]
	v_cmp_ne_u32_e64 s[0:1], 1, v32
	s_andn2_b64 vcc, exec, s[26:27]
	s_cbranch_vccnz .LBB0_309
	s_barrier
	s_barrier
	s_lshl_b32 s5, s5, 1
	v_readlane_b32 s14, v251, 26
	s_add_u32 s14, s14, s5
	v_readlane_b32 s15, v251, 28
	s_addc_u32 s15, s15, 0
	s_lshl_b32 s7, s7, 1
	s_add_u32 s89, s14, s7
	s_addc_u32 s93, s15, 0
	s_add_u32 s30, s82, s5
	v_readlane_b32 s5, v251, 32
	s_addc_u32 s35, s5, 0
	s_ashr_i32 s7, s6, 31
	s_lshl_b64 s[6:7], s[6:7], 11
	s_add_u32 vcc_lo, s89, s6
	v_lshl_add_u32 v112, v159, 10, v114
	s_addc_u32 vcc_hi, s93, s7
	v_lshl_add_u64 v[32:33], v[112:113], 1, vcc
	global_load_dwordx4 v[32:35], v[32:33], off
	s_waitcnt vmcnt(35)
	v_add_u32_e32 v84, 16, v112
	v_mov_b32_e32 v85, v113
	v_lshl_add_u64 v[36:37], v[84:85], 1, vcc
	global_load_dwordx4 v[72:75], v[36:37], off
	v_add_u32_e32 v80, 32, v112
	v_mov_b32_e32 v81, v113
	v_lshl_add_u64 v[36:37], v[80:81], 1, vcc
	global_load_dwordx4 v[68:71], v[36:37], off
	v_add_u32_e32 v82, 48, v112
	v_mov_b32_e32 v83, v113
	v_lshl_add_u64 v[36:37], v[82:83], 1, vcc
	global_load_dwordx4 v[64:67], v[36:37], off
	s_add_u32 s6, s30, s6
	s_addc_u32 s7, s35, s7
	s_add_u32 vcc_lo, s6, 0x8000
	s_addc_u32 vcc_hi, s7, 0
	v_lshlrev_b64 v[76:77], 1, v[116:117]
	v_lshl_add_u64 v[36:37], s[6:7], 0, v[76:77]
	v_lshl_add_u64 v[38:39], vcc, 0, v[76:77]
	v_lshlrev_b64 v[78:79], 1, v[118:119]
	global_load_ushort v91, v[36:37], off
	global_load_ushort v89, v[38:39], off
	global_load_ushort v87, v[36:37], off offset:64
	v_lshl_add_u64 v[38:39], vcc, 0, v[78:79]
	s_add_u32 vcc_lo, s6, 0x8800
	s_addc_u32 vcc_hi, s7, 0
	global_load_ushort v88, v[38:39], off
	global_load_ushort v94, v[36:37], off offset:2048
	v_lshl_add_u64 v[38:39], vcc, 0, v[76:77]
	global_load_ushort v92, v[38:39], off
	global_load_ushort v90, v[36:37], off offset:2112
	v_lshl_add_u64 v[36:37], vcc, 0, v[78:79]
	s_add_u32 vcc_lo, s6, 0x1000
	s_addc_u32 vcc_hi, s7, 0
	s_add_u32 s48, s6, 0x9000
	global_load_ushort v93, v[36:37], off
	s_addc_u32 s49, s7, 0
	v_lshl_add_u64 v[36:37], vcc, 0, v[76:77]
	global_load_ushort v98, v[36:37], off
	v_lshl_add_u64 v[36:37], s[48:49], 0, v[76:77]
	global_load_ushort v97, v[36:37], off
	v_lshl_add_u64 v[36:37], vcc, 0, v[78:79]
	global_load_ushort v95, v[36:37], off
	v_lshl_add_u64 v[36:37], s[48:49], 0, v[78:79]
	s_add_u32 s48, s6, 0x1800
	s_addc_u32 s49, s7, 0
	s_add_u32 vcc_lo, s6, 0x9800
	global_load_ushort v96, v[36:37], off
	s_addc_u32 vcc_hi, s7, 0
	v_lshl_add_u64 v[36:37], s[48:49], 0, v[76:77]
	global_load_ushort v102, v[36:37], off
	v_lshl_add_u64 v[36:37], vcc, 0, v[76:77]
	global_load_ushort v100, v[36:37], off
	v_lshl_add_u64 v[36:37], s[48:49], 0, v[78:79]
	s_add_u32 s48, s6, 0x4000
	s_addc_u32 s49, s7, 0
	global_load_ushort v99, v[36:37], off
	v_lshl_add_u64 v[36:37], vcc, 0, v[78:79]
	s_add_u32 vcc_lo, s6, 0xc000
	global_load_ushort v101, v[36:37], off
	s_addc_u32 vcc_hi, s7, 0
	v_lshl_add_u64 v[36:37], s[48:49], 0, v[76:77]
	global_load_ushort v107, v[36:37], off
	v_lshl_add_u64 v[36:37], vcc, 0, v[76:77]
	global_load_ushort v106, v[36:37], off
	v_lshl_add_u64 v[36:37], s[48:49], 0, v[78:79]
	s_add_u32 s48, s6, 0x4800
	s_addc_u32 s49, s7, 0
	global_load_ushort v103, v[36:37], off
	v_lshl_add_u64 v[36:37], vcc, 0, v[78:79]
	s_add_u32 vcc_lo, s6, 0xc800
	global_load_ushort v105, v[36:37], off
	s_addc_u32 vcc_hi, s7, 0
	v_lshl_add_u64 v[36:37], s[48:49], 0, v[76:77]
	global_load_ushort v111, v[36:37], off
	v_lshl_add_u64 v[36:37], vcc, 0, v[76:77]
	global_load_ushort v109, v[36:37], off
	v_lshl_add_u64 v[36:37], s[48:49], 0, v[78:79]
	s_add_u32 s48, s6, 0x5000
	s_addc_u32 s49, s7, 0
	v_lshl_add_u64 v[118:119], s[48:49], 0, v[78:79]
	global_load_ushort v108, v[36:37], off
	s_nop 0
	global_load_ushort v118, v[118:119], off
	v_lshl_add_u64 v[36:37], vcc, 0, v[78:79]
	s_add_u32 vcc_lo, s6, 0xd000
	s_addc_u32 vcc_hi, s7, 0
	v_lshl_add_u64 v[120:121], vcc, 0, v[78:79]
	global_load_ushort v110, v[36:37], off
	global_load_ushort v117, v[120:121], off
	v_lshl_add_u64 v[36:37], s[48:49], 0, v[76:77]
	global_load_ushort v116, v[36:37], off
	v_lshl_add_u64 v[36:37], vcc, 0, v[76:77]
	global_load_ushort v114, v[36:37], off
	s_waitcnt vmcnt(31)
	v_mfma_f32_32x32x16_bf16 v[32:47], v[32:35], v[60:63], 0
	s_add_u32 s48, s6, 0x5800
	s_addc_u32 s49, s7, 0
	s_add_u32 s6, s6, 0xd800
	s_addc_u32 s7, s7, 0
	v_lshl_add_u64 v[120:121], s[48:49], 0, v[78:79]
	s_waitcnt vmcnt(30)
	v_mfma_f32_32x32x16_bf16 v[32:47], v[72:75], v[56:59], v[32:47]
	v_lshl_add_u64 v[72:73], s[48:49], 0, v[76:77]
	global_load_ushort v74, v[72:73], off
	s_waitcnt vmcnt(30)
	v_mfma_f32_32x32x16_bf16 v[32:47], v[68:71], v[52:55], v[32:47]
	v_lshl_add_u64 v[68:69], s[6:7], 0, v[78:79]
	global_load_ushort v68, v[68:69], off
	v_lshl_add_u64 v[72:73], s[6:7], 0, v[76:77]
	global_load_ushort v73, v[72:73], off
	v_max_i32_e32 v69, 0xffffff80, v168
	global_load_ushort v72, v[120:121], off
	v_add_u32_e32 v69, 0x80, v69
	s_waitcnt vmcnt(32)
	v_mfma_f32_32x32x16_bf16 v[32:47], v[64:67], v[48:51], v[32:47]
	v_max_i32_e32 v64, 0xffffff7f, v168
	v_max_i32_e32 v65, 0xffffff7e, v168
	v_add_u32_e32 v64, 0x81, v64
	v_add_u32_e32 v65, 0x82, v65
	v_min_u32_e32 v69, 0xc0, v69
	v_min_u32_e32 v64, 0xc0, v64
	v_min_u32_e32 v65, 0xc0, v65
	v_lshl_add_u32 v69, v69, 2, s92
	v_lshl_add_u32 v64, v64, 2, s92
	v_lshl_add_u32 v65, v65, 2, s92
	ds_read_b32 v69, v69
	ds_read_b32 v64, v64
	ds_read_b32 v66, v65
	v_max_i32_e32 v65, 0xffffff7d, v168
	v_add_u32_e32 v65, 0x83, v65
	v_min_u32_e32 v65, 0xc0, v65
	v_lshl_add_u32 v65, v65, 2, s92
	ds_read_b32 v67, v65
	v_max_i32_e32 v65, 0xffffff78, v168
	v_add_u32_e32 v65, 0x88, v65
	v_min_u32_e32 v65, 0xc0, v65
	v_lshl_add_u32 v65, v65, 2, s92
	s_waitcnt lgkmcnt(3)
	v_add_f32_e32 v32, v32, v69
	ds_read_b32 v69, v65
	v_max_i32_e32 v65, 0xffffff77, v168
	v_add_u32_e32 v65, 0x89, v65
	v_min_u32_e32 v65, 0xc0, v65
	v_lshl_add_u32 v65, v65, 2, s92
	ds_read_b32 v70, v65
	s_waitcnt lgkmcnt(4)
	v_add_f32_e32 v65, v33, v64
	s_waitcnt lgkmcnt(3)
	v_add_f32_e32 v64, v34, v66
	s_waitcnt lgkmcnt(1)
	v_add_f32_e32 v34, v36, v69
	v_max_i32_e32 v36, 0xffffff76, v168
	s_waitcnt lgkmcnt(0)
	v_add_f32_e32 v33, v37, v70
	v_max_i32_e32 v37, 0xffffff75, v168
	v_max_i32_e32 v66, 0xffffff70, v168
	v_add_u32_e32 v36, 0x8a, v36
	v_add_u32_e32 v37, 0x8b, v37
	v_add_u32_e32 v66, 0x90, v66
	v_min_u32_e32 v36, 0xc0, v36
	v_min_u32_e32 v37, 0xc0, v37
	v_min_u32_e32 v66, 0xc0, v66
	v_lshl_add_u32 v36, v36, 2, s92
	v_lshl_add_u32 v37, v37, 2, s92
	v_lshl_add_u32 v66, v66, 2, s92
	v_add_f32_e32 v35, v35, v67
	ds_read_b32 v36, v36
	ds_read_b32 v37, v37
	ds_read_b32 v67, v66
	v_max_i32_e32 v66, 0xffffff6f, v168
	v_add_u32_e32 v66, 0x91, v66
	v_min_u32_e32 v66, 0xc0, v66
	v_lshl_add_u32 v66, v66, 2, s92
	ds_read_b32 v69, v66
	v_max_i32_e32 v66, 0xffffff6e, v168
	v_add_u32_e32 v66, 0x92, v66
	v_min_u32_e32 v66, 0xc0, v66
	v_lshl_add_u32 v66, v66, 2, s92
	ds_read_b32 v70, v66
	s_waitcnt lgkmcnt(4)
	v_add_f32_e32 v66, v38, v36
	s_waitcnt lgkmcnt(3)
	v_add_f32_e32 v39, v39, v37
	s_waitcnt lgkmcnt(2)
	v_add_f32_e32 v38, v40, v67
	s_waitcnt lgkmcnt(1)
	v_add_f32_e32 v37, v41, v69
	v_max_i32_e32 v40, 0xffffff6d, v168
	v_max_i32_e32 v41, 0xffffff68, v168
	s_waitcnt lgkmcnt(0)
	v_add_f32_e32 v36, v42, v70
	v_add_u32_e32 v40, 0x93, v40
	v_add_u32_e32 v41, 0x98, v41
	v_max_i32_e32 v42, 0xffffff67, v168
	v_max_i32_e32 v67, 0xffffff66, v168
	v_min_u32_e32 v40, 0xc0, v40
	v_min_u32_e32 v41, 0xc0, v41
	v_add_u32_e32 v42, 0x99, v42
	v_add_u32_e32 v67, 0x9a, v67
	v_lshl_add_u32 v40, v40, 2, s92
	v_lshl_add_u32 v41, v41, 2, s92
	v_min_u32_e32 v42, 0xc0, v42
	v_min_u32_e32 v67, 0xc0, v67
	ds_read_b32 v40, v40
	ds_read_b32 v41, v41
	v_lshl_add_u32 v42, v42, 2, s92
	v_lshl_add_u32 v67, v67, 2, s92
	ds_read_b32 v42, v42
	ds_read_b32 v69, v67
	v_max_i32_e32 v67, 0xffffff65, v168
	v_add_u32_e32 v67, 0x9b, v67
	v_min_u32_e32 v67, 0xc0, v67
	v_lshl_add_u32 v67, v67, 2, s92
	ds_read_b32 v70, v67
	s_waitcnt lgkmcnt(4)
	v_add_f32_e32 v67, v43, v40
	s_waitcnt lgkmcnt(3)
	v_add_f32_e32 v43, v44, v41
	v_max3_f32 v44, v32, s31, v65
	v_max3_f32 v44, v44, v64, v35
	v_max3_f32 v44, v44, v34, v33
	v_max3_f32 v44, v44, v66, v39
	v_max3_f32 v44, v44, v38, v37
	s_waitcnt lgkmcnt(2)
	v_add_f32_e32 v42, v45, v42
	v_max3_f32 v44, v44, v36, v67
	s_waitcnt lgkmcnt(1)
	v_add_f32_e32 v40, v46, v69
	s_waitcnt lgkmcnt(0)
	v_add_f32_e32 v41, v47, v70
	v_max3_f32 v44, v44, v43, v42
	v_max3_f32 v44, v44, v40, v41
	ds_bpermute_b32 v45, v194, v44
	s_waitcnt lgkmcnt(0)
	v_max3_f32 v86, v104, v44, v45
	v_cmp_gt_f32_e32 vcc, v86, v104
	s_cbranch_vccz .LBB0_306
	v_sub_f32_e32 v44, v104, v86
	v_exp_f32_e32 v69, v44
	ds_bpermute_b32 v44, v164, v69
	ds_bpermute_b32 v45, v165, v69
	ds_bpermute_b32 v46, v166, v69
	ds_bpermute_b32 v47, v167, v69
	ds_bpermute_b32 v70, v162, v69
	ds_bpermute_b32 v71, v158, v69
	ds_bpermute_b32 v120, v156, v69
	ds_bpermute_b32 v122, v152, v69
	ds_bpermute_b32 v124, v148, v69
	ds_bpermute_b32 v126, v144, v69
	ds_bpermute_b32 v128, v140, v69
	ds_bpermute_b32 v129, v138, v69
	ds_bpermute_b32 v127, v142, v69
	ds_bpermute_b32 v125, v146, v69
	ds_bpermute_b32 v123, v150, v69
	ds_bpermute_b32 v121, v154, v69
	s_waitcnt lgkmcnt(4)
	v_pk_mul_f32 v[14:15], v[14:15], v[128:129]
	s_waitcnt lgkmcnt(3)
	v_pk_mul_f32 v[12:13], v[12:13], v[126:127]
	s_waitcnt lgkmcnt(2)
	v_pk_mul_f32 v[10:11], v[10:11], v[124:125]
	s_waitcnt lgkmcnt(1)
	v_pk_mul_f32 v[8:9], v[8:9], v[122:123]
	s_waitcnt lgkmcnt(0)
	v_pk_mul_f32 v[6:7], v[6:7], v[120:121]
	v_pk_mul_f32 v[4:5], v[4:5], v[70:71]
	v_pk_mul_f32 v[2:3], v[2:3], v[46:47]
	v_pk_mul_f32 v[0:1], v[0:1], v[44:45]
	v_pk_mul_f32 v[30:31], v[30:31], v[128:129]
	v_pk_mul_f32 v[28:29], v[28:29], v[126:127]
	v_pk_mul_f32 v[26:27], v[26:27], v[124:125]
	v_pk_mul_f32 v[24:25], v[24:25], v[122:123]
	v_pk_mul_f32 v[22:23], v[22:23], v[120:121]
	v_pk_mul_f32 v[20:21], v[20:21], v[70:71]
	v_pk_mul_f32 v[18:19], v[18:19], v[46:47]
	v_pk_mul_f32 v[16:17], v[16:17], v[44:45]
	v_mul_f32_e32 v169, v169, v69
